# static priority raise: also waves 0-3 (forward direction) in ML_SCAN
# baseline (speedup 1.0000x reference)
; __device__ __forceinline__ int ltid() { int t = threadIdx.x; asm volatile("" : "+v"(t)); return t; }
; __device__ __forceinline__ unsigned pk2(float a, float b) { return cvtpk(a, b); }
; __device__ __forceinline__ void ph_ml_scan(const P& p, int j, char* smem0) {
;   const int d = ltid() >> 8;
;   char* smem = smem0 + d * MLG_BYTES;
;   bfr* sQ = (bfr*)smem; bfr* sK = sQ + 64 * QS; bfr* sVT = sK + 64 * QS; bfr* sCT = sVT + 16 * VS;
;   float* sN = (float*)(sCT + 16 * QS);
;   float* sEs = sN + 128; float* sCt = sEs + 64; float* sBc = sCt + 64; float* sWg = sBc + 64; float* sNr = sWg + 64; bfr* sNb = (bfr*)(sNr + 256); float* sMisc = (float*)(sNb + 128); bfr* sVW = (bfr*)(sMisc + 4);
;   const bfr* QKV = (const bfr*)(p.ACT + A_QKV); const float* GT = (const float*)(p.ACT + A_GATE); bfr* HS = (bfr*)(p.ACT + A_HS);
;   const float* gbias = p.ml_gate_b + (size_t)j * 32;
;   const int tid = ltid() & 255, lane = tid & 63, w = tid >> 6, l15 = lane & 15, q4 = lane >> 4;
;   for (int it = xcd_swz(); it < 256; it += gridDim.x) {
;     const int b = it >> 7, hh = (it >> 4) & 7, sl = it & 15;
;     f32x4 Cacc[2];
;     Cacc[0] = f32x4{0.f, 0.f, 0.f, 0.f}; Cacc[1] = f32x4{0.f, 0.f, 0.f, 0.f};
;     float mcur = 0.f;
;     for (int i = tid; i < 16 * QS; i += 256) sCT[i] = 0;
;     if (tid < 128) { sN[tid] = 0.f; sNb[tid] = 0; }
;     uint4 pq0, pq1, pq2, pq3, pk0, pk1, pk2, pk3, pv = uint4{0u, 0u, 0u, 0u}; float pgi = 0.f, pgf = 0.f;
.LBB0_1137:
	s_andn2_b64 vcc, exec, s[6:7]
	s_cbranch_vccnz .LBB0_1210
	v_readlane_b32 s6, v251, 21
	v_readlane_b32 s7, v251, 22
	v_mov_b32_e32 v0, v168
	v_mov_b32_e32 v6, v168
	s_andn2_b64 vcc, exec, s[6:7]
	s_cbranch_vccnz .LBB0_1210
	v_readfirstlane_b32 s6, v168
	s_lshr_b32 s6, s6, 6
	s_cmp_ge_u32 s6, 4
	s_cbranch_scc1 .Lprio_ms
	s_setprio 1
.Lprio_ms:
	s_waitcnt lgkmcnt(0)
	v_ashrrev_i32_e32 v2, 8, v0
	s_mov_b32 s6, 0xb800
	v_mad_i32_i24 v91, v2, s6, 0
	v_readlane_b32 s6, v254, 57
	v_readlane_b32 s40, v253, 49
	v_readlane_b32 s7, v254, 58
	v_readlane_b32 s42, v253, 51
	v_readlane_b32 s43, v253, 52
	v_bfe_u32 v149, v6, 4, 4
	s_mov_b32 s8, s6
	s_ashr_i32 s9, s6, 31
	v_writelane_b32 v254, s6, 57
	v_cmp_lt_u32_e64 s[42:43], s15, v0
	v_lshlrev_b32_e32 v3, 3, v6
	v_cmp_gt_u32_e64 s[48:49], s65, v0
	v_mul_u32_u24_e32 v0, 0x88, v149
	s_waitcnt vmcnt(0)
	v_mul_i32_i24_e32 v11, 0xb800, v2
	v_writelane_b32 v254, s7, 58
	s_lshl_b64 s[6:7], s[8:9], 7
	v_and_b32_e32 v13, 63, v6
	v_and_b32_e32 v12, 0x78, v3
	v_and_b32_e32 v90, 8, v3
	v_bitop3_b32 v3, v6, 63, v6 bitop3:0xc
	v_lshlrev_b32_e32 v92, 4, v2
	v_lshl_add_u32 v2, v0, 1, v91
	v_readlane_b32 s41, v253, 50
	s_add_u32 s6, s40, s6
	v_and_b32_e32 v7, 0xff, v6
	s_movk_i32 s8, 0x80
	v_cndmask_b32_e64 v154, v3, v13, s[48:49]
	v_lshl_add_u32 v3, v12, 1, v2
	s_addc_u32 s7, s41, s7
	v_and_b32_e32 v8, 15, v6
	v_cmp_gt_u32_e64 s[40:41], s8, v7
	v_readlane_b32 s8, v251, 39
	v_add_u32_e32 v155, 0x1100, v3
	v_add_u32_e32 v156, 0x2200, v3
	v_add_u32_e32 v157, 0x3300, v3
	v_lshrrev_b32_e32 v3, 2, v6
	v_bfe_u32 v9, v6, 6, 2
	v_ashrrev_i32_e32 v93, 31, v92
	v_readlane_b32 s9, v251, 40
	v_lshlrev_b32_e32 v0, 4, v8
	v_and_b32_e32 v14, 12, v3
	v_lshlrev_b32_e32 v3, 7, v149
	v_lshlrev_b32_e32 v10, 3, v8
	v_lshl_add_u64 v[94:95], v[92:93], 2, s[8:9]
	v_add_u32_e32 v93, v2, v0
	v_lshl_or_b32 v158, v9, 4, v8
	v_sub_u32_e32 v2, v2, v3
	s_movk_i32 s8, 0x110
	v_bfe_u32 v153, v6, 1, 7
	v_add_u32_e32 v159, v2, v10
	v_and_b32_e32 v162, 48, v6
	v_mul_u32_u24_e32 v15, 0x90, v8
	v_and_b32_e32 v2, 3, v6
	v_mul_u32_u24_e32 v16, 0x110, v8
	v_mad_u32_u24 v17, v8, s8, v91
	v_cmp_eq_u32_e64 s[52:53], 0, v8
	v_lshl_or_b32 v8, v9, 5, v8
	v_mul_u32_u24_e32 v9, 0x90, v90
	v_and_b32_e32 v6, 0xfe, v6
	v_cmp_le_u32_e32 vcc, v14, v158
	v_add3_u32 v165, v91, v9, v6
	v_lshl_add_u32 v188, v8, 2, v91
	v_cndmask_b32_e64 v6, 0, 1, vcc
	v_cmp_ge_u32_e32 vcc, v14, v158
	v_cmp_eq_u32_e64 s[50:51], 0, v2
	v_cmp_gt_u32_e64 s[54:55], 16, v13
	v_cndmask_b32_e64 v9, 0, 1, vcc
	v_cndmask_b32_e64 v6, v9, v6, s[48:49]
	v_and_b32_e32 v6, 1, v6
	v_cmp_eq_u32_e64 s[58:59], 1, v6
	v_or_b32_e32 v6, 1, v14
	v_cmp_lt_u32_e32 vcc, v14, v158
	v_cmp_eq_u32_e64 s[56:57], 0, v13
	v_readlane_b32 s44, v253, 53
	v_cndmask_b32_e64 v9, 0, 1, vcc
	v_cmp_ge_u32_e32 vcc, v6, v158
	v_readlane_b32 s45, v253, 54
	v_readlane_b32 s46, v253, 55
	v_cndmask_b32_e64 v6, 0, 1, vcc
	v_cndmask_b32_e64 v6, v6, v9, s[48:49]
	v_and_b32_e32 v6, 1, v6
	v_cmp_eq_u32_e64 s[60:61], 1, v6
	v_or_b32_e32 v6, 2, v14
	v_cmp_le_u32_e32 vcc, v6, v158
	v_readlane_b32 s47, v253, 56
	v_lshlrev_b32_e32 v147, 1, v7
	v_cndmask_b32_e64 v9, 0, 1, vcc
	v_cmp_ge_u32_e32 vcc, v6, v158
	v_cndmask_b32_e64 v2, 0, v181, s[50:51]
	v_cmp_gt_u32_e64 s[44:45], 64, v7
	v_cndmask_b32_e64 v6, 0, 1, vcc
	v_cndmask_b32_e64 v6, v6, v9, s[48:49]
	v_and_b32_e32 v6, 1, v6
	v_cmp_eq_u32_e64 s[62:63], 1, v6
	v_or_b32_e32 v6, 3, v14
	v_cmp_le_u32_e32 vcc, v6, v158
	v_cmp_lt_u32_e64 s[46:47], 63, v7
	v_lshl_add_u64 v[96:97], s[26:27], 0, v[0:1]
	v_cndmask_b32_e64 v9, 0, 1, vcc
	v_cmp_ge_u32_e32 vcc, v6, v158
	v_add_u32_e32 v160, v91, v0
	v_mad_u32_u24 v161, v158, s8, v91
	v_cndmask_b32_e64 v6, 0, 1, vcc
	v_cndmask_b32_e64 v6, v6, v9, s[48:49]
	v_and_b32_e32 v6, 1, v6
	v_cmp_eq_u32_e64 s[64:65], 1, v6
	v_or_b32_e32 v6, 16, v14
	v_cmp_le_u32_e32 vcc, v6, v158
	v_add_u32_e32 v163, v91, v162
	v_mul_i32_i24_e32 v0, 0xfffffef4, v158
	v_cndmask_b32_e64 v9, 0, 1, vcc
	v_cmp_ge_u32_e32 vcc, v6, v158
	v_perm_b32 v2, v2, v2, s94
	v_lshl_add_u32 v167, v7, 2, v91
	v_cndmask_b32_e64 v6, 0, 1, vcc
	v_cndmask_b32_e64 v6, v6, v9, s[48:49]
	v_and_b32_e32 v6, 1, v6
	v_cmp_eq_u32_e64 s[66:67], 1, v6
	v_or_b32_e32 v6, 17, v14
	v_cmp_le_u32_e32 vcc, v6, v158
; __device__ __forceinline__ void ph_ml_scan(const P& p, int j, char* smem0) {
;     ...
;       for (int a = 0; a < 4; a++) { const float4 ex4 = *(const float4*)(sEs + 16 * a + 4 * q4); const float exv[4] = {ex4.x, ex4.y, ex4.z, ex4.w};
; #pragma unroll
;         for (int jj = 0; jj < 4; jj++) { int rs_ = 16 * a + 4 * q4 + jj; bool valid = d == 0 ? rs_ <= rt : rs_ >= rt;
;           float wv = valid ? ect * exv[jj] : 0.f; sacc[a][jj] = sacc[a][jj] * wv; } }
	v_or_b32_e32 v11, v11, v147
	v_readlane_b32 s8, v253, 34
	v_cndmask_b32_e64 v9, 0, 1, vcc
	v_cmp_ge_u32_e32 vcc, v6, v158
	v_add_u32_e32 v148, v91, v147
	v_or_b32_e32 v150, 16, v149
	v_cndmask_b32_e64 v6, 0, 1, vcc
	v_cndmask_b32_e64 v6, v6, v9, s[48:49]
	v_and_b32_e32 v6, 1, v6
	v_cmp_eq_u32_e64 s[68:69], 1, v6
	v_or_b32_e32 v6, 18, v14
	v_cmp_le_u32_e32 vcc, v6, v158
	v_or_b32_e32 v151, 32, v149
	v_or_b32_e32 v152, 48, v149
	v_cndmask_b32_e64 v9, 0, 1, vcc
	v_cmp_ge_u32_e32 vcc, v6, v158
	v_lshl_add_u32 v164, v14, 2, v91
	v_mov_b32_e32 v3, v2
	v_cndmask_b32_e64 v6, 0, 1, vcc
	v_cndmask_b32_e64 v6, v6, v9, s[48:49]
	v_and_b32_e32 v6, 1, v6
	v_cmp_eq_u32_e64 s[70:71], 1, v6
	v_or_b32_e32 v6, 19, v14
	v_cmp_le_u32_e32 vcc, v6, v158
	v_mov_b32_e32 v4, v2
	v_mov_b32_e32 v5, v2
	v_cndmask_b32_e64 v9, 0, 1, vcc
	v_cmp_ge_u32_e32 vcc, v6, v158
	v_lshl_add_u32 v166, v154, 2, v91
	v_add_u32_e32 v190, s8, v11
	v_cndmask_b32_e64 v6, 0, 1, vcc
	v_cndmask_b32_e64 v6, v6, v9, s[48:49]
	v_and_b32_e32 v6, 1, v6
	v_cmp_eq_u32_e64 s[72:73], 1, v6
	v_or_b32_e32 v6, 32, v14
	v_cmp_le_u32_e32 vcc, v6, v158
	v_lshlrev_b32_e32 v98, 1, v10
	v_lshlrev_b32_e32 v100, 1, v12
	v_cndmask_b32_e64 v9, 0, 1, vcc
	v_cmp_ge_u32_e32 vcc, v6, v158
	v_lshlrev_b32_e32 v102, 1, v14
	v_add_u32_e32 v191, v163, v16
	v_cndmask_b32_e64 v6, 0, 1, vcc
	v_cndmask_b32_e64 v6, v6, v9, s[48:49]
	v_and_b32_e32 v6, 1, v6
	v_cmp_eq_u32_e64 s[74:75], 1, v6
	v_or_b32_e32 v6, 33, v14
	v_cmp_le_u32_e32 vcc, v6, v158
	v_add_u32_e32 v192, v17, v162
	v_add_u32_e32 v195, v161, v0
	v_cndmask_b32_e64 v9, 0, 1, vcc
	v_cmp_ge_u32_e32 vcc, v6, v158
	v_readlane_b32 s19, v253, 21
	s_nop 0
	v_cndmask_b32_e64 v6, 0, 1, vcc
	v_cndmask_b32_e64 v6, v6, v9, s[48:49]
	v_and_b32_e32 v6, 1, v6
	v_cmp_eq_u32_e64 s[76:77], 1, v6
	v_or_b32_e32 v6, 34, v14
	v_cmp_le_u32_e32 vcc, v6, v158
	s_nop 1
	v_cndmask_b32_e64 v9, 0, 1, vcc
	v_cmp_ge_u32_e32 vcc, v6, v158
	s_nop 1
	v_cndmask_b32_e64 v6, 0, 1, vcc
	v_cndmask_b32_e64 v6, v6, v9, s[48:49]
	v_and_b32_e32 v6, 1, v6
	v_cmp_eq_u32_e64 s[78:79], 1, v6
	v_or_b32_e32 v6, 35, v14
	v_cmp_le_u32_e32 vcc, v6, v158
	s_nop 1
	v_cndmask_b32_e64 v9, 0, 1, vcc
	v_cmp_ge_u32_e32 vcc, v6, v158
	s_nop 1
	v_cndmask_b32_e64 v6, 0, 1, vcc
	v_cndmask_b32_e64 v6, v6, v9, s[48:49]
	v_and_b32_e32 v6, 1, v6
	v_cmp_eq_u32_e64 s[80:81], 1, v6
	v_or_b32_e32 v6, 48, v14
	v_cmp_le_u32_e32 vcc, v6, v158
	s_nop 1
	v_cndmask_b32_e64 v9, 0, 1, vcc
	v_cmp_ge_u32_e32 vcc, v6, v158
	s_nop 1
	v_cndmask_b32_e64 v6, 0, 1, vcc
	v_cndmask_b32_e64 v6, v6, v9, s[48:49]
	v_and_b32_e32 v6, 1, v6
	v_cmp_eq_u32_e64 s[82:83], 1, v6
	v_or_b32_e32 v6, 49, v14
	v_cmp_le_u32_e32 vcc, v6, v158
	s_nop 1
	v_cndmask_b32_e64 v9, 0, 1, vcc
	v_cmp_ge_u32_e32 vcc, v6, v158
	s_nop 1
	v_cndmask_b32_e64 v6, 0, 1, vcc
	v_cndmask_b32_e64 v6, v6, v9, s[48:49]
	v_and_b32_e32 v6, 1, v6
	v_cmp_eq_u32_e64 s[84:85], 1, v6
	v_or_b32_e32 v6, 50, v14
	v_cmp_le_u32_e32 vcc, v6, v158
	s_nop 1
	v_cndmask_b32_e64 v9, 0, 1, vcc
	v_cmp_ge_u32_e32 vcc, v6, v158
	s_nop 1
	v_cndmask_b32_e64 v6, 0, 1, vcc
	v_cndmask_b32_e64 v6, v6, v9, s[48:49]
	v_and_b32_e32 v6, 1, v6
	v_cmp_eq_u32_e64 s[86:87], 1, v6
	v_or_b32_e32 v6, 51, v14
	v_cmp_le_u32_e32 vcc, v6, v158
	s_nop 1
	v_cndmask_b32_e64 v9, 0, 1, vcc
	v_cmp_ge_u32_e32 vcc, v6, v158
	s_nop 1
	v_cndmask_b32_e64 v6, 0, 1, vcc
	v_cndmask_b32_e64 v6, v6, v9, s[48:49]
	v_and_b32_e32 v6, 1, v6
	v_cmp_eq_u32_e64 s[88:89], 1, v6
	v_lshlrev_b32_e32 v6, 1, v14
	v_add3_u32 v187, v91, v15, v6
	v_lshlrev_b32_e32 v6, 1, v8
	v_add_u32_e32 v13, v91, v6
	v_sub_u32_e32 v18, v188, v6
	v_sub_u32_e32 v6, 0x87f, v7
	v_lshrrev_b32_e32 v6, 8, v6
	v_mul_u32_u24_e32 v15, 0x110, v14
	v_add_u32_e32 v7, 4, v6
	v_and_b32_e32 v189, 28, v7
	v_mov_b32_e32 v7, v6
	v_mov_b32_e32 v8, v6
	v_mov_b32_e32 v9, v6
	v_add_u32_e32 v193, v13, v15
	v_add_u32_e32 v194, v18, v15
	v_and_b32_e32 v201, 15, v168
	v_lshrrev_b32_e32 v202, 2, v201
	v_bfe_u32 v203, v168, 4, 2
	v_lshl_add_u32 v202, v203, 2, v202
	v_mul_u32_u24_e32 v202, 0x110, v202
	v_and_b32_e32 v201, 3, v201
	v_lshlrev_b32_e32 v201, 3, v201
	v_bfe_u32 v203, v168, 6, 2
	v_lshl_add_u32 v201, v203, 6, v201
	v_add3_u32 v200, v91, v202, v201
	v_add_u32_e32 v200, 0x4400, v200
	s_branch .LBB0_1141
